# gate-up/pair tile loop: next-tile index arithmetic moved from the tile header into the MFMA shadow of the peeled first iteration (branch-free)
# speedup vs baseline: 1.0079x; 1.0014x over previous
; #define PG8_STAGE(bufoff, gbase, voff) do { _Pragma("unroll") for (int _i = 0; _i < 2; ++_i) { \
;         const unsigned _m0 = ldsb + (unsigned)((bufoff) + _i * 8192); const char* _gb = (const char*)(gbase); \
;         asm volatile("s_mov_b32 m0, %0\n\ts_nop 0\n\tglobal_load_lds_dwordx4 %1, %2" :: "s"(_m0), "v"((voff)[_i]), "s"(_gb) : "m0", "memory"); } } while (0)
; #define PG8_LDA(dst, b, h) do { _Pragma("unroll") for (int m = 0; m < 4; ++m) _Pragma("unroll") for (int k = 0; k < 2; ++k) dst[m][k] = *(const LAS bf16x8*)(lds + PG8_SA(b, h) + aoff + m * 2048 + k * 1024); } while (0)
; #define PG8_LDB(dst, b, h) do { _Pragma("unroll") for (int n = 0; n < 2; ++n) _Pragma("unroll") for (int k = 0; k < 2; ++k) dst[n][k] = *(const LAS bf16x8*)(lds + PG8_SB(b, h) + boff + n * 2048 + k * 1024); } while (0)
;     __device__ bool next(int i, Unit& u) const {
;         const long L = (long)i * G + c; if (L >= nwg) return false;
;         int wgid = (int)L; { const int q = nwg / NXCD, r = nwg % NXCD, xcd = wgid % NXCD, off = wgid / NXCD; wgid = (xcd < r ? xcd * (q + 1) : r * (q + 1) + (xcd - r) * q) + off; }
;         const int nig = WGM * nN, gid = wgid / nig, fm = gid * WGM, gsz = (nM - fm) < WGM ? (nM - fm) : WGM;
;         u.pm = fm + ((wgid % nig) % gsz); u.pn = (wgid % nig) / gsz; return true;
;     }
; template <class Epi, bool ALIGN_EPI>
; __device__ __forceinline__ void gemm_phase(LAS unsigned char* lds, const Gemm g, const StaticOrder& S, const Epi& E) {
;     ...
;         const bool has_next = S.next(ui + 1, nxt);
;         const char* nA = has_next ? (const char*)g.A + (size_t)nxt.pm * tstepA + (size_t)nxt.pn * g.a_pn_off * 2 + (size_t)(nxt.pm >> 4) * g.a_adj : cA; const char* nB = has_next ? (const char*)g.Bt + (size_t)nxt.pn * tstepB : cB;
;         for (int t = 0; t < nt; t += 2) {
;             const bool last = (t == nt - 2);
;             const char* a1 = cA + (size_t)(t + 1) * kstep;
;             const char* a2 = last ? nA : cA + (size_t)(t + 2) * kstep; const char* b2 = last ? nB : cB + (size_t)(t + 2) * kstep;
;             const char* a3 = a2 + kstep; const char* b3 = b2 + kstep;
;             PG8_LDB(B0, 0, 0); PG8_LDB(B1, 0, 1); PG8_SCHED; PG8_LDA(At, 0, 0); PG8_STAGE(PG8_SA(1, 1), a1 + hstepA, voffA);
;             PG8_WAIT_V(8); PG8_WAIT_L(0); PG8_BAR; PG8_MMA(0, 0, At, B0); PG8_MMA(0, 1, At, B1); PG8_BAR; PG8_SCHED;
.LBB0_305:
	s_add_u32 s41, s56, 0x100
	s_addc_u32 s49, s57, 0
	s_add_u32 s92, s58, 0x40080
	s_addc_u32 s93, s59, 0
	s_mov_b32 s50, -2
	s_add_u32 s30, s92, 0xfffc0080
	s_addc_u32 s31, s93, -1
	s_cmp_eq_u32 s50, 12
	s_cselect_b32 s60, s5, s30
	s_cselect_b32 s61, s4, s31
	s_cselect_b32 s58, s37, s41
	s_cselect_b32 s59, s35, s49
	s_add_u32 s56, s60, 0x80
	s_addc_u32 s57, s61, 0
	s_mov_b32 m0, s67
	s_nop 0
	global_load_lds_dwordx4 v0, s[92:93]
	s_nop 0
	s_mov_b32 m0, s65
	s_nop 0
	global_load_lds_dwordx4 v181, s[92:93]
	s_waitcnt vmcnt(8)
	s_waitcnt lgkmcnt(0)
	s_barrier
	s_setprio 1
	s_waitcnt lgkmcnt(0)
	v_mfma_f32_16x16x32_bf16 v[142:145], v[74:77], v[162:165], 0
	s_mul_i32 s4, s85, s27
	s_mul_hi_u32 s5, s85, s87
	s_add_i32 s5, s5, s4
	v_mfma_f32_16x16x32_bf16 v[142:145], v[94:97], v[166:169], v[142:145]
	s_mul_i32 s4, s85, s87
	s_add_u32 s4, s4, s16
	s_addc_u32 s5, s5, s68
	v_mfma_f32_16x16x32_bf16 v[138:141], v[114:117], v[162:165], 0
	v_mov_b64_e32 v[192:193], s[46:47]
	v_cmp_lt_i64_e64 s[8:9], s[4:5], v[192:193]
	s_ashr_i32 s5, s4, 31
	v_mfma_f32_16x16x32_bf16 v[138:141], v[134:137], v[166:169], v[138:141]
	s_lshr_b32 s5, s5, 29
	s_add_i32 s5, s4, s5
	s_ashr_i32 s30, s5, 3
	v_mfma_f32_16x16x32_bf16 v[130:133], v[146:149], v[162:165], 0
	s_and_b32 s5, s5, -8
	s_sub_i32 s4, s4, s5
	s_lshr_b32 s5, s4, 31
	v_mfma_f32_16x16x32_bf16 v[130:133], v[150:153], v[166:169], v[130:133]
	s_or_b32 s5, s78, s5
	s_mul_i32 s4, s5, s4
	s_add_i32 s4, s4, s30
	v_mfma_f32_16x16x32_bf16 v[126:129], v[154:157], v[162:165], 0
	s_abs_i32 s30, s4
	v_readlane_b32 s31, v254, 48
	s_mul_hi_u32 s31, s30, s31
	v_mfma_f32_16x16x32_bf16 v[126:129], v[158:161], v[166:169], v[126:129]
	s_mul_i32 s34, s31, s26
	s_sub_i32 s30, s30, s34
	s_ashr_i32 s5, s4, 31
	v_mfma_f32_16x16x32_bf16 v[106:109], v[154:157], v[170:173], 0
	s_add_i32 s34, s31, 1
	s_sub_i32 s35, s30, s26
	s_cmp_ge_u32 s30, s26
	v_mfma_f32_16x16x32_bf16 v[106:109], v[158:161], v[174:177], v[106:109]
	s_cselect_b32 s31, s34, s31
	s_cselect_b32 s30, s35, s30
	s_add_i32 s34, s31, 1
	v_mfma_f32_16x16x32_bf16 v[110:113], v[146:149], v[170:173], 0
	s_cmp_ge_u32 s30, s26
	s_cselect_b32 s30, s34, s31
	s_xor_b32 s30, s30, s5
	v_mfma_f32_16x16x32_bf16 v[110:113], v[150:153], v[174:177], v[110:113]
	s_sub_i32 s5, s30, s5
	s_lshl_b32 s30, s5, 3
	s_sub_i32 s31, 0x80, s30
	v_mfma_f32_16x16x32_bf16 v[118:121], v[114:117], v[170:173], 0
	s_min_i32 s31, s31, 8
	s_abs_i32 s34, s31
	v_cvt_f32_u32_e32 v192, s34
	v_mfma_f32_16x16x32_bf16 v[118:121], v[134:137], v[174:177], v[118:121]
	s_sub_i32 s36, 0, s34
	s_mul_i32 s5, s5, s26
	s_sub_i32 s4, s4, s5
	v_mfma_f32_16x16x32_bf16 v[122:125], v[74:77], v[170:173], 0
	v_rcp_iflag_f32_e32 v192, v192
	s_abs_i32 s35, s4
	s_xor_b32 s5, s4, s31
	v_mfma_f32_16x16x32_bf16 v[122:125], v[94:97], v[174:177], v[122:125]
	s_ashr_i32 s5, s5, 31
	v_mul_f32_e32 v192, 0x4f7ffffe, v192
	v_cvt_u32_f32_e32 v192, v192
	v_mfma_f32_16x16x32_bf16 v[102:105], v[74:77], v[188:191], 0
	s_nop 0
	v_readfirstlane_b32 s37, v192
	s_mul_i32 s36, s36, s37
	v_mfma_f32_16x16x32_bf16 v[102:105], v[94:97], v[202:205], v[102:105]
	s_mul_hi_u32 s36, s37, s36
	s_add_i32 s37, s37, s36
	s_mul_hi_u32 s36, s35, s37
	v_mfma_f32_16x16x32_bf16 v[98:101], v[114:117], v[188:191], 0
	s_mul_i32 s37, s36, s34
	s_sub_i32 s35, s35, s37
	s_add_i32 s37, s36, 1
	v_mfma_f32_16x16x32_bf16 v[98:101], v[134:137], v[202:205], v[98:101]
	s_sub_i32 s38, s35, s34
	s_cmp_ge_u32 s35, s34
	s_cselect_b32 s36, s37, s36
	v_mfma_f32_16x16x32_bf16 v[90:93], v[146:149], v[188:191], 0
	s_cselect_b32 s35, s38, s35
	s_add_i32 s37, s36, 1
	s_cmp_ge_u32 s35, s34
	v_mfma_f32_16x16x32_bf16 v[90:93], v[150:153], v[202:205], v[90:93]
	s_cselect_b32 s34, s37, s36
	s_xor_b32 s34, s34, s5
	s_sub_i32 s34, s34, s5
	v_mfma_f32_16x16x32_bf16 v[86:89], v[154:157], v[188:191], 0
	s_mul_i32 s5, s34, s31
	s_sub_i32 s4, s4, s5
	s_add_i32 s36, s4, s30
	v_mfma_f32_16x16x32_bf16 v[86:89], v[158:161], v[202:205], v[86:89]
	s_ashr_i32 s37, s36, 31
	s_lshl_b64 s[4:5], s[36:37], 19
	s_add_u32 s38, s18, s4
	v_mfma_f32_16x16x32_bf16 v[66:69], v[154:157], v[206:209], 0
	s_addc_u32 s39, s19, s5
	s_and_b64 s[4:5], s[8:9], exec
	s_cselect_b32 s4, s39, s59
	v_mfma_f32_16x16x32_bf16 v[66:69], v[158:161], v[210:213], v[66:69]
	s_cselect_b32 s5, s38, s58
	s_ashr_i32 s35, s34, 31
	s_lshl_b64 s[30:31], s[34:35], 19
	v_mfma_f32_16x16x32_bf16 v[70:73], v[146:149], v[206:209], 0
	s_add_u32 s90, s1, s30
	s_addc_u32 s91, s14, s31
	s_and_b64 s[30:31], s[8:9], exec
	v_mfma_f32_16x16x32_bf16 v[70:73], v[150:153], v[210:213], v[70:73]
	s_cselect_b32 s35, s91, s57
	s_cselect_b32 s37, s90, s56
	v_mfma_f32_16x16x32_bf16 v[78:81], v[114:117], v[206:209], 0
	v_mfma_f32_16x16x32_bf16 v[78:81], v[134:137], v[210:213], v[78:81]
	v_mfma_f32_16x16x32_bf16 v[82:85], v[74:77], v[206:209], 0
	v_mfma_f32_16x16x32_bf16 v[82:85], v[94:97], v[210:213], v[82:85]
	s_setprio 0
	s_barrier
	ds_read_b128 v[162:165], v186 offset:16384
	ds_read_b128 v[166:169], v186 offset:17408
	ds_read_b128 v[170:173], v186 offset:18432
	ds_read_b128 v[174:177], v186 offset:19456
	ds_read_b128 v[188:191], v186 offset:20480
	ds_read_b128 v[202:205], v186 offset:21504
	ds_read_b128 v[206:209], v186 offset:22528
	ds_read_b128 v[210:213], v186 offset:23552
	s_mov_b32 m0, s29
	s_nop 0
	global_load_lds_dwordx4 v180, s[58:59]
	s_add_u32 s30, s58, 0x40000
	s_mov_b32 m0, s42
	s_nop 0
	global_load_lds_dwordx4 v182, s[58:59]
	s_addc_u32 s31, s59, 0
	s_mov_b32 m0, s43
	s_nop 0
	global_load_lds_dwordx4 v180, s[30:31]
	s_nop 0
	s_mov_b32 m0, s44
	s_nop 0
	global_load_lds_dwordx4 v182, s[30:31]
	s_nop 0
	s_mov_b32 m0, s15
	s_nop 0
	global_load_lds_dwordx4 v0, s[60:61]
	s_nop 0
	s_mov_b32 m0, s45
	s_nop 0
	global_load_lds_dwordx4 v181, s[60:61]
	s_waitcnt vmcnt(8)
	s_waitcnt lgkmcnt(0)
	s_barrier
; #define PG8_STAGE(bufoff, gbase, voff) do { _Pragma("unroll") for (int _i = 0; _i < 2; ++_i) { \
;         const unsigned _m0 = ldsb + (unsigned)((bufoff) + _i * 8192); const char* _gb = (const char*)(gbase); \
;         asm volatile("s_mov_b32 m0, %0\n\ts_nop 0\n\tglobal_load_lds_dwordx4 %1, %2" :: "s"(_m0), "v"((voff)[_i]), "s"(_gb) : "m0", "memory"); } } while (0)
; #define PG8_LDA(dst, b, h) do { _Pragma("unroll") for (int m = 0; m < 4; ++m) _Pragma("unroll") for (int k = 0; k < 2; ++k) dst[m][k] = *(const LAS bf16x8*)(lds + PG8_SA(b, h) + aoff + m * 2048 + k * 1024); } while (0)
; #define PG8_LDB(dst, b, h) do { _Pragma("unroll") for (int n = 0; n < 2; ++n) _Pragma("unroll") for (int k = 0; k < 2; ++k) dst[n][k] = *(const LAS bf16x8*)(lds + PG8_SB(b, h) + boff + n * 2048 + k * 1024); } while (0)
; #define PG8_MMA(ai, bj, At, Bt) do { __builtin_amdgcn_s_setprio(1); _Pragma("unroll") for (int m = 0; m < 4; ++m) _Pragma("unroll") for (int n = 0; n < 2; ++n) _Pragma("unroll") for (int k = 0; k < 2; ++k) \
;         acc[ai][bj][m][n] = __builtin_amdgcn_mfma_f32_16x16x32_bf16(Bt[n][k], At[m][k], acc[ai][bj][m][n], 0, 0, 0); __builtin_amdgcn_s_setprio(0); } while (0)
; #define PG8_WAIT_V(n) asm volatile("s_waitcnt vmcnt(" #n ")" ::: "memory")
; #define PG8_WAIT_L(n) asm volatile("s_waitcnt lgkmcnt(" #n ")" ::: "memory")
; #define PG8_BAR __builtin_amdgcn_s_barrier()
; #define PG8_SCHED __builtin_amdgcn_sched_barrier(0)
; template <class Epi, bool ALIGN_EPI>
; __device__ __forceinline__ void gemm_phase(LAS unsigned char* lds, const Gemm g, const StaticOrder& S, const Epi& E) {
;     ...
;             PG8_LDA(At, 0, 1); PG8_STAGE(PG8_SB(0, 0), b2, voffB); PG8_STAGE(PG8_SB(0, 1), b2 + hstepB, voffB); PG8_STAGE(PG8_SA(0, 0), a2, voffA);
;             PG8_WAIT_V(8); PG8_WAIT_L(0); PG8_BAR; PG8_MMA(1, 0, At, B0); PG8_MMA(1, 1, At, B1); PG8_BAR; PG8_SCHED;
;             PG8_LDB(B0, 1, 0); PG8_LDB(B1, 1, 1); PG8_SCHED; PG8_LDA(At, 1, 0); PG8_STAGE(PG8_SA(0, 1), a2 + hstepA, voffA);
;             PG8_WAIT_V(8); PG8_WAIT_L(0); PG8_BAR; PG8_MMA(0, 0, At, B0); PG8_MMA(0, 1, At, B1); PG8_BAR; PG8_SCHED;
	s_setprio 1
	s_waitcnt lgkmcnt(0)
	v_mfma_f32_16x16x32_bf16 v[62:65], v[74:77], v[162:165], 0
	v_mfma_f32_16x16x32_bf16 v[62:65], v[94:97], v[166:169], v[62:65]
	v_mfma_f32_16x16x32_bf16 v[58:61], v[114:117], v[162:165], 0
	v_mfma_f32_16x16x32_bf16 v[58:61], v[134:137], v[166:169], v[58:61]
	v_mfma_f32_16x16x32_bf16 v[54:57], v[146:149], v[162:165], 0
	v_mfma_f32_16x16x32_bf16 v[54:57], v[150:153], v[166:169], v[54:57]
	v_mfma_f32_16x16x32_bf16 v[50:53], v[154:157], v[162:165], 0
	v_mfma_f32_16x16x32_bf16 v[50:53], v[158:161], v[166:169], v[50:53]
	v_mfma_f32_16x16x32_bf16 v[34:37], v[154:157], v[170:173], 0
	v_mfma_f32_16x16x32_bf16 v[34:37], v[158:161], v[174:177], v[34:37]
	v_mfma_f32_16x16x32_bf16 v[38:41], v[146:149], v[170:173], 0
	v_mfma_f32_16x16x32_bf16 v[38:41], v[150:153], v[174:177], v[38:41]
	v_mfma_f32_16x16x32_bf16 v[42:45], v[114:117], v[170:173], 0
	v_mfma_f32_16x16x32_bf16 v[42:45], v[134:137], v[174:177], v[42:45]
	v_mfma_f32_16x16x32_bf16 v[46:49], v[74:77], v[170:173], 0
	v_mfma_f32_16x16x32_bf16 v[46:49], v[94:97], v[174:177], v[46:49]
	v_mfma_f32_16x16x32_bf16 v[30:33], v[74:77], v[188:191], 0
	v_mfma_f32_16x16x32_bf16 v[30:33], v[94:97], v[202:205], v[30:33]
	v_mfma_f32_16x16x32_bf16 v[26:29], v[114:117], v[188:191], 0
	v_mfma_f32_16x16x32_bf16 v[26:29], v[134:137], v[202:205], v[26:29]
	v_mfma_f32_16x16x32_bf16 v[22:25], v[146:149], v[188:191], 0
	v_mfma_f32_16x16x32_bf16 v[22:25], v[150:153], v[202:205], v[22:25]
	v_mfma_f32_16x16x32_bf16 v[18:21], v[154:157], v[188:191], 0
	v_mfma_f32_16x16x32_bf16 v[18:21], v[158:161], v[202:205], v[18:21]
	v_mfma_f32_16x16x32_bf16 v[2:5], v[154:157], v[206:209], 0
	v_mfma_f32_16x16x32_bf16 v[2:5], v[158:161], v[210:213], v[2:5]
	v_mfma_f32_16x16x32_bf16 v[6:9], v[146:149], v[206:209], 0
	v_mfma_f32_16x16x32_bf16 v[6:9], v[150:153], v[210:213], v[6:9]
	v_mfma_f32_16x16x32_bf16 v[10:13], v[114:117], v[206:209], 0
	v_mfma_f32_16x16x32_bf16 v[10:13], v[134:137], v[210:213], v[10:13]
	v_mfma_f32_16x16x32_bf16 v[14:17], v[74:77], v[206:209], 0
	v_mfma_f32_16x16x32_bf16 v[14:17], v[94:97], v[210:213], v[14:17]
	s_setprio 0
	s_barrier
	v_add_u32_e32 v134, 0x18000, v185
	v_add_u32_e32 v158, 0x1c000, v185
	ds_read_b128 v[74:77], v134
	ds_read_b128 v[94:97], v134 offset:1024
	ds_read_b128 v[114:117], v134 offset:2048
	ds_read_b128 v[134:137], v134 offset:3072
	ds_read_b128 v[146:149], v158
	ds_read_b128 v[150:153], v158 offset:1024
	ds_read_b128 v[154:157], v158 offset:2048
	ds_read_b128 v[158:161], v158 offset:3072
	ds_read_b128 v[162:165], v186 offset:32768
	ds_read_b128 v[166:169], v186 offset:33792
	ds_read_b128 v[170:173], v186 offset:34816
	ds_read_b128 v[174:177], v186 offset:35840
	ds_read_b128 v[188:191], v186 offset:36864
	ds_read_b128 v[202:205], v186 offset:37888
	ds_read_b128 v[206:209], v186 offset:38912
	ds_read_b128 v[210:213], v186 offset:39936
	s_add_u32 s30, s60, 0x40000
	s_addc_u32 s31, s61, 0
	s_mov_b32 m0, s55
	s_nop 0
	global_load_lds_dwordx4 v0, s[30:31]
	s_nop 0
	s_mov_b32 m0, s88
	s_nop 0
	global_load_lds_dwordx4 v181, s[30:31]
	s_waitcnt vmcnt(8)
	s_waitcnt lgkmcnt(0)
	s_barrier
	s_setprio 1
	s_waitcnt lgkmcnt(0)
	v_mfma_f32_16x16x32_bf16 v[142:145], v[74:77], v[162:165], v[142:145]
	v_mfma_f32_16x16x32_bf16 v[142:145], v[94:97], v[166:169], v[142:145]
	v_mfma_f32_16x16x32_bf16 v[138:141], v[114:117], v[162:165], v[138:141]
	v_mfma_f32_16x16x32_bf16 v[138:141], v[134:137], v[166:169], v[138:141]
	v_mfma_f32_16x16x32_bf16 v[130:133], v[146:149], v[162:165], v[130:133]
	v_mfma_f32_16x16x32_bf16 v[130:133], v[150:153], v[166:169], v[130:133]
	v_mfma_f32_16x16x32_bf16 v[126:129], v[154:157], v[162:165], v[126:129]
	v_mfma_f32_16x16x32_bf16 v[126:129], v[158:161], v[166:169], v[126:129]
	v_mfma_f32_16x16x32_bf16 v[106:109], v[154:157], v[170:173], v[106:109]
	v_mfma_f32_16x16x32_bf16 v[106:109], v[158:161], v[174:177], v[106:109]
	v_mfma_f32_16x16x32_bf16 v[110:113], v[146:149], v[170:173], v[110:113]
	v_mfma_f32_16x16x32_bf16 v[110:113], v[150:153], v[174:177], v[110:113]
	v_mfma_f32_16x16x32_bf16 v[118:121], v[114:117], v[170:173], v[118:121]
	v_mfma_f32_16x16x32_bf16 v[118:121], v[134:137], v[174:177], v[118:121]
	v_mfma_f32_16x16x32_bf16 v[122:125], v[74:77], v[170:173], v[122:125]
	v_mfma_f32_16x16x32_bf16 v[122:125], v[94:97], v[174:177], v[122:125]
	v_mfma_f32_16x16x32_bf16 v[102:105], v[74:77], v[188:191], v[102:105]
	v_mfma_f32_16x16x32_bf16 v[102:105], v[94:97], v[202:205], v[102:105]
	v_mfma_f32_16x16x32_bf16 v[98:101], v[114:117], v[188:191], v[98:101]
	v_mfma_f32_16x16x32_bf16 v[98:101], v[134:137], v[202:205], v[98:101]
	v_mfma_f32_16x16x32_bf16 v[90:93], v[146:149], v[188:191], v[90:93]
	v_mfma_f32_16x16x32_bf16 v[90:93], v[150:153], v[202:205], v[90:93]
	v_mfma_f32_16x16x32_bf16 v[86:89], v[154:157], v[188:191], v[86:89]
	v_mfma_f32_16x16x32_bf16 v[86:89], v[158:161], v[202:205], v[86:89]
	v_mfma_f32_16x16x32_bf16 v[66:69], v[154:157], v[206:209], v[66:69]
	v_mfma_f32_16x16x32_bf16 v[66:69], v[158:161], v[210:213], v[66:69]
	v_mfma_f32_16x16x32_bf16 v[70:73], v[146:149], v[206:209], v[70:73]
	v_mfma_f32_16x16x32_bf16 v[70:73], v[150:153], v[210:213], v[70:73]
	v_mfma_f32_16x16x32_bf16 v[78:81], v[114:117], v[206:209], v[78:81]
	v_mfma_f32_16x16x32_bf16 v[78:81], v[134:137], v[210:213], v[78:81]
	v_mfma_f32_16x16x32_bf16 v[82:85], v[74:77], v[206:209], v[82:85]
	v_mfma_f32_16x16x32_bf16 v[82:85], v[94:97], v[210:213], v[82:85]
	s_setprio 0
	s_barrier
; #define PG8_STAGE(bufoff, gbase, voff) do { _Pragma("unroll") for (int _i = 0; _i < 2; ++_i) { \
;         const unsigned _m0 = ldsb + (unsigned)((bufoff) + _i * 8192); const char* _gb = (const char*)(gbase); \
;         asm volatile("s_mov_b32 m0, %0\n\ts_nop 0\n\tglobal_load_lds_dwordx4 %1, %2" :: "s"(_m0), "v"((voff)[_i]), "s"(_gb) : "m0", "memory"); } } while (0)
; #define PG8_LDA(dst, b, h) do { _Pragma("unroll") for (int m = 0; m < 4; ++m) _Pragma("unroll") for (int k = 0; k < 2; ++k) dst[m][k] = *(const LAS bf16x8*)(lds + PG8_SA(b, h) + aoff + m * 2048 + k * 1024); } while (0)
; #define PG8_MMA(ai, bj, At, Bt) do { __builtin_amdgcn_s_setprio(1); _Pragma("unroll") for (int m = 0; m < 4; ++m) _Pragma("unroll") for (int n = 0; n < 2; ++n) _Pragma("unroll") for (int k = 0; k < 2; ++k) \
;         acc[ai][bj][m][n] = __builtin_amdgcn_mfma_f32_16x16x32_bf16(Bt[n][k], At[m][k], acc[ai][bj][m][n], 0, 0, 0); __builtin_amdgcn_s_setprio(0); } while (0)
; #define PG8_WAIT_V(n) asm volatile("s_waitcnt vmcnt(" #n ")" ::: "memory")
; #define PG8_WAIT_L(n) asm volatile("s_waitcnt lgkmcnt(" #n ")" ::: "memory")
; #define PG8_BAR __builtin_amdgcn_s_barrier()
; #define PG8_SCHED __builtin_amdgcn_sched_barrier(0)
; template <class Epi, bool ALIGN_EPI>
; __device__ __forceinline__ void gemm_phase(LAS unsigned char* lds, const Gemm g, const StaticOrder& S, const Epi& E) {
;     ...
;             PG8_LDA(At, 1, 1); PG8_STAGE(PG8_SB(1, 0), b3, voffB); PG8_STAGE(PG8_SB(1, 1), b3 + hstepB, voffB); PG8_STAGE(PG8_SA(1, 0), a3, voffA);
;             PG8_WAIT_V(8); PG8_WAIT_L(0); PG8_BAR; PG8_MMA(1, 0, At, B0); PG8_MMA(1, 1, At, B1); PG8_BAR; PG8_SCHED;
;         }
	ds_read_b128 v[162:165], v186 offset:49152
	ds_read_b128 v[166:169], v186 offset:50176
	ds_read_b128 v[170:173], v186 offset:51200
	ds_read_b128 v[174:177], v186 offset:52224
	ds_read_b128 v[188:191], v186 offset:53248
	ds_read_b128 v[202:205], v186 offset:54272
	ds_read_b128 v[206:209], v186 offset:55296
	ds_read_b128 v[210:213], v186 offset:56320
	s_add_u32 s30, s58, 0x80
	s_addc_u32 s31, s59, 0
	s_mov_b32 m0, s94
	s_nop 0
	global_load_lds_dwordx4 v180, s[30:31]
	s_nop 0
	s_mov_b32 m0, s95
	s_nop 0
	global_load_lds_dwordx4 v182, s[30:31]
	s_add_u32 s30, s58, 0x40080
	s_addc_u32 s31, s59, 0
	s_mov_b32 m0, s17
	s_nop 0
	global_load_lds_dwordx4 v180, s[30:31]
	s_nop 0
	s_mov_b32 m0, s53
	s_nop 0
	global_load_lds_dwordx4 v182, s[30:31]
	s_nop 0
	s_mov_b32 m0, s96
	s_nop 0
	global_load_lds_dwordx4 v0, s[56:57]
	s_nop 0
	s_mov_b32 m0, s97
	s_nop 0
	global_load_lds_dwordx4 v181, s[56:57]
	s_waitcnt vmcnt(8)
	s_waitcnt lgkmcnt(0)
	s_barrier
	s_setprio 1
	s_waitcnt lgkmcnt(0)
	v_mfma_f32_16x16x32_bf16 v[62:65], v[74:77], v[162:165], v[62:65]
	v_mfma_f32_16x16x32_bf16 v[62:65], v[94:97], v[166:169], v[62:65]
	v_mfma_f32_16x16x32_bf16 v[58:61], v[114:117], v[162:165], v[58:61]
	v_mfma_f32_16x16x32_bf16 v[58:61], v[134:137], v[166:169], v[58:61]
	v_mfma_f32_16x16x32_bf16 v[54:57], v[146:149], v[162:165], v[54:57]
	v_mfma_f32_16x16x32_bf16 v[54:57], v[150:153], v[166:169], v[54:57]
	v_mfma_f32_16x16x32_bf16 v[50:53], v[154:157], v[162:165], v[50:53]
	v_mfma_f32_16x16x32_bf16 v[50:53], v[158:161], v[166:169], v[50:53]
	v_mfma_f32_16x16x32_bf16 v[34:37], v[154:157], v[170:173], v[34:37]
	v_mfma_f32_16x16x32_bf16 v[34:37], v[158:161], v[174:177], v[34:37]
	v_mfma_f32_16x16x32_bf16 v[38:41], v[146:149], v[170:173], v[38:41]
	v_mfma_f32_16x16x32_bf16 v[38:41], v[150:153], v[174:177], v[38:41]
	v_mfma_f32_16x16x32_bf16 v[42:45], v[114:117], v[170:173], v[42:45]
	v_mfma_f32_16x16x32_bf16 v[42:45], v[134:137], v[174:177], v[42:45]
	v_mfma_f32_16x16x32_bf16 v[46:49], v[74:77], v[170:173], v[46:49]
	v_mfma_f32_16x16x32_bf16 v[46:49], v[94:97], v[174:177], v[46:49]
	v_mfma_f32_16x16x32_bf16 v[30:33], v[74:77], v[188:191], v[30:33]
	v_mfma_f32_16x16x32_bf16 v[30:33], v[94:97], v[202:205], v[30:33]
	v_mfma_f32_16x16x32_bf16 v[26:29], v[114:117], v[188:191], v[26:29]
	v_mfma_f32_16x16x32_bf16 v[26:29], v[134:137], v[202:205], v[26:29]
	v_mfma_f32_16x16x32_bf16 v[22:25], v[146:149], v[188:191], v[22:25]
	v_mfma_f32_16x16x32_bf16 v[22:25], v[150:153], v[202:205], v[22:25]
	v_mfma_f32_16x16x32_bf16 v[18:21], v[154:157], v[188:191], v[18:21]
	v_mfma_f32_16x16x32_bf16 v[18:21], v[158:161], v[202:205], v[18:21]
	v_mfma_f32_16x16x32_bf16 v[2:5], v[154:157], v[206:209], v[2:5]
	v_mfma_f32_16x16x32_bf16 v[2:5], v[158:161], v[210:213], v[2:5]
	v_mfma_f32_16x16x32_bf16 v[6:9], v[146:149], v[206:209], v[6:9]
	v_mfma_f32_16x16x32_bf16 v[6:9], v[150:153], v[210:213], v[6:9]
	v_mfma_f32_16x16x32_bf16 v[10:13], v[114:117], v[206:209], v[10:13]
	v_mfma_f32_16x16x32_bf16 v[10:13], v[134:137], v[210:213], v[10:13]
	v_mfma_f32_16x16x32_bf16 v[14:17], v[74:77], v[206:209], v[14:17]
	v_mfma_f32_16x16x32_bf16 v[14:17], v[94:97], v[210:213], v[14:17]
	s_setprio 0
	s_barrier
	s_add_i32 s50, s50, 2
	s_add_u32 s41, s41, 0x100
	s_addc_u32 s49, s49, 0
	s_add_u32 s92, s92, 0x100
	s_addc_u32 s93, s93, 0
	s_cmp_gt_u32 s50, 13
